# v21 + sub-LN combine phase: the wave's next row is requested while the current row is reduced (staging registers, flag cleared on skipped rows)
# speedup vs baseline: 1.0135x; 1.0034x over previous
; __device__ __forceinline__ void phase_combine(const Params& p, const Ctx& c, int l, bool last) {
;     ...
;   const float lam_init = 0.8f - 0.6f * expf(-0.3f * (float)l);
;   float lam;
;   { const float a1 = p.lam_q1[l * 128 + c.lane] * p.lam_k1[l * 128 + c.lane] + p.lam_q1[l * 128 + 64 + c.lane] * p.lam_k1[l * 128 + 64 + c.lane];
;     const float a2 = p.lam_q2[l * 128 + c.lane] * p.lam_k2[l * 128 + c.lane] + p.lam_q2[l * 128 + 64 + c.lane] * p.lam_k2[l * 128 + 64 + c.lane];
;     lam = expf(wave_sum(a1)) - expf(wave_sum(a2)) + lam_init; }
;   const f32x4 gs = *(const f32x4*)(p.g_subln + (size_t)l * 256 + c.lane * 4);
;   for (int row = c.gwave; row < TT; row += c.nwave) { const int t = row % TPB; if (last && t < CTXL) continue;
.LBB0_722:
	v_mov_b32_e32 v1, v220
	s_mov_b32 s8, s95
	s_load_dwordx8 s[0:7], s[84:85], 0x60
	v_and_b32_e32 v10, 63, v1
	v_readlane_b32 s9, v250, 8
	v_mov_b32_e32 v3, v0
	v_ashrrev_i32_e32 v1, 6, v1
	v_lshl_or_b32 v2, s9, 7, v10
	v_lshlrev_b64 v[2:3], 2, v[2:3]
	s_waitcnt lgkmcnt(0)
	v_lshl_add_u64 v[4:5], s[0:1], 0, v[2:3]
	v_lshl_add_u64 v[6:7], s[2:3], 0, v[2:3]
	global_load_dword v8, v[4:5], off
	global_load_dword v9, v[4:5], off offset:256
	global_load_dword v11, v[6:7], off
	s_nop 0
	global_load_dword v7, v[6:7], off offset:256
	v_lshl_add_u64 v[4:5], s[4:5], 0, v[2:3]
	v_lshl_add_u64 v[2:3], s[6:7], 0, v[2:3]
	global_load_dword v12, v[2:3], off offset:256
	global_load_dword v13, v[4:5], off offset:256
	s_nop 0
	global_load_dword v4, v[4:5], off
	s_nop 0
	global_load_dword v2, v[2:3], off
	v_lshl_add_u32 v6, s8, 3, v1
	v_cmp_gt_i32_e32 vcc, s38, v6
	s_waitcnt vmcnt(0)
	v_mul_f32_e32 v1, v9, v7
	v_mul_f32_e32 v3, v13, v12
	v_fmac_f32_e32 v1, v8, v11
	v_fmac_f32_e32 v3, v4, v2
	s_nop 0
	v_add_f32_dpp v1, v1, v1 quad_perm:[1,0,3,2] row_mask:0xf bank_mask:0xf bound_ctrl:1
	v_add_f32_dpp v2, v3, v3 quad_perm:[1,0,3,2] row_mask:0xf bank_mask:0xf bound_ctrl:1
	s_nop 0
	v_add_f32_dpp v1, v1, v1 quad_perm:[2,3,0,1] row_mask:0xf bank_mask:0xf bound_ctrl:1
	v_add_f32_dpp v2, v2, v2 quad_perm:[2,3,0,1] row_mask:0xf bank_mask:0xf bound_ctrl:1
	s_nop 0
	v_add_f32_dpp v1, v1, v1 row_half_mirror row_mask:0xf bank_mask:0xf bound_ctrl:1
	v_add_f32_dpp v2, v2, v2 row_half_mirror row_mask:0xf bank_mask:0xf bound_ctrl:1
	s_nop 0
	v_add_f32_dpp v1, v1, v1 row_mirror row_mask:0xf bank_mask:0xf bound_ctrl:1
	v_add_f32_dpp v2, v2, v2 row_mirror row_mask:0xf bank_mask:0xf bound_ctrl:1
	v_readlane_b32 s4, v1, 0
	v_readlane_b32 s10, v1, 16
	v_readlane_b32 s5, v1, 32
	v_readlane_b32 s11, v1, 48
	v_readlane_b32 s0, v2, 0
	v_readlane_b32 s2, v2, 16
	v_readlane_b32 s1, v2, 32
	v_readlane_b32 s3, v2, 48
	s_and_saveexec_b64 s[6:7], vcc
	s_cbranch_execz .LBB0_727
	s_load_dwordx2 s[12:13], s[84:85], 0x80
	s_load_dwordx2 s[8:9], s[84:85], 0x108
	v_readlane_b32 s17, v250, 8
	s_lshl_b32 s30, s17, 8
	s_lshl_b64 s[14:15], s[30:31], 2
	s_waitcnt lgkmcnt(0)
	s_add_u32 s12, s12, s14
	s_addc_u32 s13, s13, s15
	v_lshlrev_b32_e32 v1, 4, v10
	global_load_dwordx4 v[2:5], v1, s[12:13]
	v_cvt_f32_u32_e32 v1, s17
	s_mov_b32 s12, 0x3fb8aa3b
	s_mov_b32 s13, 0xc2ce8ed0
	v_mul_f32_e32 v1, 0xbe99999a, v1
	v_mul_f32_e32 v7, 0x3fb8aa3b, v1
	v_fma_f32 v8, v1, s12, -v7
	v_rndne_f32_e32 v9, v7
	v_fmac_f32_e32 v8, 0x32a5705f, v1
	v_sub_f32_e32 v7, v7, v9
	v_add_f32_e32 v7, v7, v8
	v_exp_f32_e32 v7, v7
	v_cvt_i32_f32_e32 v8, v9
	v_mov_b32_e32 v9, s11
	v_add_f32_e32 v9, s5, v9
	v_cmp_ngt_f32_e32 vcc, s13, v1
	v_ldexp_f32 v7, v7, v8
	v_mov_b32_e32 v8, s10
	v_add_f32_e32 v8, s4, v8
	v_add_f32_e32 v8, v8, v9
	v_mul_f32_e32 v9, 0x3fb8aa3b, v8
	v_fma_f32 v11, v8, s12, -v9
	v_rndne_f32_e32 v12, v9
	v_fmac_f32_e32 v11, 0x32a5705f, v8
	v_sub_f32_e32 v9, v9, v12
	v_add_f32_e32 v9, v9, v11
	v_exp_f32_e32 v9, v9
	v_cvt_i32_f32_e32 v11, v12
	s_mov_b32 s4, 0x42b17218
	v_cndmask_b32_e32 v7, 0, v7, vcc
	v_cmp_nlt_f32_e32 vcc, s4, v1
	s_nop 1
	v_cndmask_b32_e32 v1, v230, v7, vcc
	v_ldexp_f32 v7, v9, v11
	v_mov_b32_e32 v9, s2
	v_mov_b32_e32 v11, s3
	v_add_f32_e32 v9, s0, v9
	v_add_f32_e32 v11, s1, v11
	v_add_f32_e32 v9, v9, v11
	v_mul_f32_e32 v11, 0x3fb8aa3b, v9
	v_fma_f32 v12, v9, s12, -v11
	v_rndne_f32_e32 v13, v11
	v_fmac_f32_e32 v12, 0x32a5705f, v9
	v_sub_f32_e32 v11, v11, v13
	v_add_f32_e32 v11, v11, v12
	v_exp_f32_e32 v11, v11
	v_cvt_i32_f32_e32 v12, v13
	v_cmp_ngt_f32_e32 vcc, s13, v8
	v_fmamk_f32 v1, v1, 0xbf19999a, v225
	s_mov_b64 s[0:1], 0x21cd0000
	v_cndmask_b32_e32 v7, 0, v7, vcc
	v_cmp_nlt_f32_e32 vcc, s4, v8
	v_ldexp_f32 v8, v11, v12
	s_nop 0
	v_cndmask_b32_e32 v7, v230, v7, vcc
	v_cmp_ngt_f32_e32 vcc, s13, v9
	s_nop 1
	v_cndmask_b32_e32 v8, 0, v8, vcc
	v_cmp_nlt_f32_e32 vcc, s4, v9
	s_nop 1
	v_cndmask_b32_e32 v8, v230, v8, vcc
	v_sub_f32_e32 v7, v7, v8
	v_add_f32_e32 v8, v1, v7
	v_ashrrev_i32_e32 v7, 31, v6
	v_lshlrev_b64 v[12:13], 12, v[6:7]
	v_lshl_or_b32 v12, v10, 3, v12
	v_lshl_add_u64 v[10:11], s[8:9], 0, v[12:13]
	v_sub_f32_e32 v1, 1.0, v1
	v_mov_b32_e32 v9, v8
	v_lshl_add_u64 v[10:11], v[10:11], 0, s[0:1]
	s_mov_b64 s[8:9], 0
	s_mov_b32 s100, 0
	s_branch .LBB0_725

; __device__ __forceinline__ unsigned cvtpk(float lo, float hi) { unsigned r; asm volatile("v_cvt_pk_bf16_f32 %0, %1, %2" : "=v"(r) : "v"(lo), "v"(hi)); return r; }
; __device__ __forceinline__ void phase_combine(const Params& p, const Ctx& c, int l, bool last) {
;     ...
;   for (int row = c.gwave; row < TT; row += c.nwave) { const int t = row % TPB; if (last && t < CTXL) continue;
;     const bf16_t* orow = O + (size_t)row * DM; bf16_t* crow_ = Cat + (size_t)row * DM;
; #pragma unroll
;     for (int h = 0; h < 4; ++h) { const u32x2 a = *(const u32x2*)(orow + (h * 2) * 256 + c.lane * 4), bq = *(const u32x2*)(orow + (h * 2 + 1) * 256 + c.lane * 4);
;       f32x4 o; o[0] = __uint_as_float(a[0] << 16) - lam * __uint_as_float(bq[0] << 16); o[1] = __uint_as_float(a[0] & 0xffff0000u) - lam * __uint_as_float(bq[0] & 0xffff0000u);
;       o[2] = __uint_as_float(a[1] << 16) - lam * __uint_as_float(bq[1] << 16); o[3] = __uint_as_float(a[1] & 0xffff0000u) - lam * __uint_as_float(bq[1] & 0xffff0000u);
;       const float ss = wave_sum(o[0] * o[0] + o[1] * o[1] + o[2] * o[2] + o[3] * o[3]); const float r = rsqrtf(ss * (1.f / 256.f) + 1e-5f) * (1.f - lam_init);
;       o = o * r * gs; u32x2 w = {cvtpk(o[0], o[1]), cvtpk(o[2], o[3])}; *(u32x2*)(crow_ + h * 256 + c.lane * 4) = w; }
.LBB0_725:
	s_mov_b32 s101, s100
	s_mov_b32 s100, 0
	v_mul_hi_i32 v7, v6, s94
	v_lshrrev_b32_e32 v12, 31, v7
	v_ashrrev_i32_e32 v7, 11, v7
	v_add_u32_e32 v7, v7, v12
	v_mul_i32_i24_e32 v7, 0x1100, v7
	v_sub_u32_e32 v7, v6, v7
	v_cmp_lt_i32_e32 vcc, s27, v7
	s_or_b64 s[0:1], s[52:53], vcc
	s_and_saveexec_b64 s[10:11], s[0:1]
	s_cbranch_execz .LBB0_724
	s_mov_b32 s4, 0x800000
	v_add_co_u32_e32 v12, vcc, 0xeb401000, v10
	s_nop 1
	v_addc_co_u32_e32 v13, vcc, -1, v11, vcc
	s_cmp_eq_u32 s101, 1
	s_cbranch_scc1 .Lcmb_have
	global_load_dwordx2 v[24:25], v[12:13], off offset:-4096
	global_load_dwordx2 v[26:27], v[12:13], off offset:-3584
	global_load_dwordx2 v[28:29], v[12:13], off offset:-3072
	global_load_dwordx2 v[30:31], v[12:13], off offset:-2560
	global_load_dwordx2 v[32:33], v[12:13], off offset:-2048
	global_load_dwordx2 v[34:35], v[12:13], off offset:-1536
	global_load_dwordx2 v[36:37], v[12:13], off offset:-1024
	global_load_dwordx2 v[38:39], v[12:13], off offset:-512
	s_branch .Lcmb_go
.Lcmb_have:
	s_waitcnt vmcnt(4)
	v_mov_b64_e32 v[24:25], v[40:41]
	v_mov_b64_e32 v[26:27], v[42:43]
	v_mov_b64_e32 v[28:29], v[44:45]
	v_mov_b64_e32 v[30:31], v[46:47]
	v_mov_b64_e32 v[32:33], v[48:49]
	v_mov_b64_e32 v[34:35], v[50:51]
	v_mov_b64_e32 v[36:37], v[52:53]
	v_mov_b64_e32 v[38:39], v[54:55]
.Lcmb_go:
	v_readlane_b32 s2, v250, 9
	v_readlane_b32 s3, v250, 10
	s_mov_b32 s100, 1
	s_nop 1
	v_lshl_add_u64 v[56:57], v[12:13], 0, s[2:3]
	global_load_dwordx2 v[40:41], v[56:57], off offset:-4096
	global_load_dwordx2 v[42:43], v[56:57], off offset:-3584
	global_load_dwordx2 v[44:45], v[56:57], off offset:-3072
	global_load_dwordx2 v[46:47], v[56:57], off offset:-2560
	global_load_dwordx2 v[48:49], v[56:57], off offset:-2048
	global_load_dwordx2 v[50:51], v[56:57], off offset:-1536
	global_load_dwordx2 v[52:53], v[56:57], off offset:-1024
	global_load_dwordx2 v[54:55], v[56:57], off offset:-512
	s_waitcnt vmcnt(14)
	v_lshlrev_b32_e32 v18, 16, v24
	v_and_b32_e32 v19, 0xffff0000, v24
	v_lshlrev_b32_e32 v14, 16, v25
	v_and_b32_e32 v15, 0xffff0000, v25
	v_lshlrev_b32_e32 v20, 16, v26
	v_and_b32_e32 v21, 0xffff0000, v26
	v_lshlrev_b32_e32 v16, 16, v27
	v_and_b32_e32 v17, 0xffff0000, v27
	v_pk_fma_f32 v[18:19], v[8:9], v[20:21], v[18:19] neg_lo:[1,0,0] neg_hi:[1,0,0]
	v_pk_fma_f32 v[14:15], v[8:9], v[16:17], v[14:15] neg_lo:[1,0,0] neg_hi:[1,0,0]
	v_pk_mul_f32 v[16:17], v[18:19], v[18:19]
	v_pk_mul_f32 v[20:21], v[14:15], v[14:15]
	v_add_f32_e32 v7, v16, v17
	v_add_f32_e32 v7, v20, v7
	v_add_f32_e32 v7, v21, v7
	s_nop 1
	v_add_f32_dpp v7, v7, v7 quad_perm:[1,0,3,2] row_mask:0xf bank_mask:0xf bound_ctrl:1
	s_nop 1
	v_add_f32_dpp v7, v7, v7 quad_perm:[2,3,0,1] row_mask:0xf bank_mask:0xf bound_ctrl:1
	s_nop 1
	v_add_f32_dpp v7, v7, v7 row_half_mirror row_mask:0xf bank_mask:0xf bound_ctrl:1
	s_nop 1
	v_add_f32_dpp v7, v7, v7 row_mirror row_mask:0xf bank_mask:0xf bound_ctrl:1
	s_nop 0
	v_readlane_b32 s2, v7, 16
	v_readlane_b32 s3, v7, 48
	v_readlane_b32 s0, v7, 0
	v_readlane_b32 s1, v7, 32
	v_mov_b32_e32 v16, s2
	v_mov_b32_e32 v17, s3
	v_pk_add_f32 v[16:17], s[0:1], v[16:17]
	s_nop 0
	v_add_f32_e32 v7, v16, v17
	v_fmamk_f32 v7, v7, 0x3b800000, v226
	v_mul_f32_e32 v16, 0x4b800000, v7
	v_cmp_gt_f32_e32 vcc, s4, v7
	s_nop 1
	v_cndmask_b32_e32 v7, v7, v16, vcc
	v_rsq_f32_e32 v7, v7
	s_nop 0
	v_mul_f32_e32 v16, 0x45800000, v7
	v_cndmask_b32_e32 v7, v7, v16, vcc
	v_mul_f32_e32 v16, v1, v7
	v_pk_mul_f32 v[18:19], v[18:19], v[16:17] op_sel_hi:[1,0]
	v_pk_mul_f32 v[14:15], v[14:15], v[16:17] op_sel_hi:[1,0]
	v_pk_mul_f32 v[16:17], v[2:3], v[18:19]
	v_pk_mul_f32 v[14:15], v[4:5], v[14:15]
	v_cvt_pk_bf16_f32 v16, v16, v17
	s_nop 0
	v_cvt_pk_bf16_f32 v17, v14, v15
	s_waitcnt vmcnt(12)
	v_lshlrev_b32_e32 v20, 16, v28
	v_and_b32_e32 v21, 0xffff0000, v28
	v_lshlrev_b32_e32 v22, 16, v30
	v_and_b32_e32 v23, 0xffff0000, v30
	v_lshlrev_b32_e32 v14, 16, v29
	v_and_b32_e32 v15, 0xffff0000, v29
	v_lshlrev_b32_e32 v18, 16, v31
	v_and_b32_e32 v19, 0xffff0000, v31
	v_pk_fma_f32 v[20:21], v[8:9], v[22:23], v[20:21] neg_lo:[1,0,0] neg_hi:[1,0,0]
	v_pk_fma_f32 v[14:15], v[8:9], v[18:19], v[14:15] neg_lo:[1,0,0] neg_hi:[1,0,0]
	v_pk_mul_f32 v[18:19], v[20:21], v[20:21]
	v_pk_mul_f32 v[22:23], v[14:15], v[14:15]
	v_add_f32_e32 v7, v18, v19
	v_add_f32_e32 v7, v22, v7
	v_add_f32_e32 v7, v23, v7
	global_store_dwordx2 v[10:11], v[16:17], off
	s_nop 0
	v_add_f32_dpp v7, v7, v7 quad_perm:[1,0,3,2] row_mask:0xf bank_mask:0xf bound_ctrl:1
	s_nop 1
	v_add_f32_dpp v7, v7, v7 quad_perm:[2,3,0,1] row_mask:0xf bank_mask:0xf bound_ctrl:1
	s_nop 1
	v_add_f32_dpp v7, v7, v7 row_half_mirror row_mask:0xf bank_mask:0xf bound_ctrl:1
	s_nop 1
	v_add_f32_dpp v7, v7, v7 row_mirror row_mask:0xf bank_mask:0xf bound_ctrl:1
	s_nop 0
	v_readlane_b32 s2, v7, 16
	v_readlane_b32 s3, v7, 48
	v_readlane_b32 s0, v7, 0
	v_readlane_b32 s1, v7, 32
	v_mov_b32_e32 v18, s2
	v_mov_b32_e32 v19, s3
	v_pk_add_f32 v[18:19], s[0:1], v[18:19]
	s_nop 0
	v_add_f32_e32 v7, v18, v19
	v_fmamk_f32 v7, v7, 0x3b800000, v226
	v_mul_f32_e32 v18, 0x4b800000, v7
	v_cmp_gt_f32_e32 vcc, s4, v7
	s_nop 1
	v_cndmask_b32_e32 v7, v7, v18, vcc
	v_rsq_f32_e32 v7, v7
	s_nop 0
	v_mul_f32_e32 v16, 0x45800000, v7
	v_cndmask_b32_e32 v7, v7, v16, vcc
	v_mul_f32_e32 v16, v1, v7
	v_pk_mul_f32 v[18:19], v[20:21], v[16:17] op_sel_hi:[1,0]
	v_pk_mul_f32 v[14:15], v[14:15], v[16:17] op_sel_hi:[1,0]
	v_pk_mul_f32 v[16:17], v[2:3], v[18:19]
	v_pk_mul_f32 v[14:15], v[4:5], v[14:15]
	v_cvt_pk_bf16_f32 v16, v16, v17
	s_nop 0
	v_cvt_pk_bf16_f32 v17, v14, v15
	s_waitcnt vmcnt(11)
; __device__ __forceinline__ unsigned cvtpk(float lo, float hi) { unsigned r; asm volatile("v_cvt_pk_bf16_f32 %0, %1, %2" : "=v"(r) : "v"(lo), "v"(hi)); return r; }
; __device__ __forceinline__ void phase_combine(const Params& p, const Ctx& c, int l, bool last) {
;     ...
;     for (int h = 0; h < 4; ++h) { const u32x2 a = *(const u32x2*)(orow + (h * 2) * 256 + c.lane * 4), bq = *(const u32x2*)(orow + (h * 2 + 1) * 256 + c.lane * 4);
;       f32x4 o; o[0] = __uint_as_float(a[0] << 16) - lam * __uint_as_float(bq[0] << 16); o[1] = __uint_as_float(a[0] & 0xffff0000u) - lam * __uint_as_float(bq[0] & 0xffff0000u);
;       o[2] = __uint_as_float(a[1] << 16) - lam * __uint_as_float(bq[1] << 16); o[3] = __uint_as_float(a[1] & 0xffff0000u) - lam * __uint_as_float(bq[1] & 0xffff0000u);
;       const float ss = wave_sum(o[0] * o[0] + o[1] * o[1] + o[2] * o[2] + o[3] * o[3]); const float r = rsqrtf(ss * (1.f / 256.f) + 1e-5f) * (1.f - lam_init);
;       o = o * r * gs; u32x2 w = {cvtpk(o[0], o[1]), cvtpk(o[2], o[3])}; *(u32x2*)(crow_ + h * 256 + c.lane * 4) = w; }
	v_lshlrev_b32_e32 v20, 16, v32
	v_and_b32_e32 v21, 0xffff0000, v32
	v_lshlrev_b32_e32 v22, 16, v34
	v_and_b32_e32 v23, 0xffff0000, v34
	v_lshlrev_b32_e32 v14, 16, v33
	v_and_b32_e32 v15, 0xffff0000, v33
	v_lshlrev_b32_e32 v18, 16, v35
	v_and_b32_e32 v19, 0xffff0000, v35
	v_pk_fma_f32 v[20:21], v[8:9], v[22:23], v[20:21] neg_lo:[1,0,0] neg_hi:[1,0,0]
	v_pk_fma_f32 v[14:15], v[8:9], v[18:19], v[14:15] neg_lo:[1,0,0] neg_hi:[1,0,0]
	v_pk_mul_f32 v[18:19], v[20:21], v[20:21]
	v_pk_mul_f32 v[22:23], v[14:15], v[14:15]
	v_add_f32_e32 v7, v18, v19
	v_add_f32_e32 v7, v22, v7
	v_add_f32_e32 v7, v23, v7
	global_store_dwordx2 v[10:11], v[16:17], off offset:512
	s_nop 0
	v_add_f32_dpp v7, v7, v7 quad_perm:[1,0,3,2] row_mask:0xf bank_mask:0xf bound_ctrl:1
	s_nop 1
	v_add_f32_dpp v7, v7, v7 quad_perm:[2,3,0,1] row_mask:0xf bank_mask:0xf bound_ctrl:1
	s_nop 1
	v_add_f32_dpp v7, v7, v7 row_half_mirror row_mask:0xf bank_mask:0xf bound_ctrl:1
	s_nop 1
	v_add_f32_dpp v7, v7, v7 row_mirror row_mask:0xf bank_mask:0xf bound_ctrl:1
	s_nop 0
	v_readlane_b32 s2, v7, 16
	v_readlane_b32 s3, v7, 48
	v_readlane_b32 s0, v7, 0
	v_readlane_b32 s1, v7, 32
	v_mov_b32_e32 v18, s2
	v_mov_b32_e32 v19, s3
	v_pk_add_f32 v[18:19], s[0:1], v[18:19]
	s_nop 0
	v_add_f32_e32 v7, v18, v19
	v_fmamk_f32 v7, v7, 0x3b800000, v226
	v_mul_f32_e32 v18, 0x4b800000, v7
	v_cmp_gt_f32_e32 vcc, s4, v7
	s_nop 1
	v_cndmask_b32_e32 v7, v7, v18, vcc
	v_rsq_f32_e32 v7, v7
	s_nop 0
	v_mul_f32_e32 v16, 0x45800000, v7
	v_cndmask_b32_e32 v7, v7, v16, vcc
	v_mul_f32_e32 v16, v1, v7
	v_pk_mul_f32 v[18:19], v[20:21], v[16:17] op_sel_hi:[1,0]
	v_pk_mul_f32 v[14:15], v[14:15], v[16:17] op_sel_hi:[1,0]
	v_pk_mul_f32 v[16:17], v[2:3], v[18:19]
	v_pk_mul_f32 v[14:15], v[4:5], v[14:15]
	v_cvt_pk_bf16_f32 v16, v16, v17
	s_nop 0
	v_cvt_pk_bf16_f32 v17, v14, v15
	s_waitcnt vmcnt(10)
	v_lshlrev_b32_e32 v18, 16, v36
	v_and_b32_e32 v19, 0xffff0000, v36
	v_lshlrev_b32_e32 v20, 16, v38
	v_and_b32_e32 v21, 0xffff0000, v38
	v_lshlrev_b32_e32 v14, 16, v37
	v_and_b32_e32 v15, 0xffff0000, v37
	v_lshlrev_b32_e32 v12, 16, v39
	v_and_b32_e32 v13, 0xffff0000, v39
	v_pk_fma_f32 v[18:19], v[8:9], v[20:21], v[18:19] neg_lo:[1,0,0] neg_hi:[1,0,0]
	v_pk_fma_f32 v[12:13], v[8:9], v[12:13], v[14:15] neg_lo:[1,0,0] neg_hi:[1,0,0]
	v_pk_mul_f32 v[14:15], v[18:19], v[18:19]
	v_pk_mul_f32 v[20:21], v[12:13], v[12:13]
	v_add_f32_e32 v7, v14, v15
	v_add_f32_e32 v7, v20, v7
	v_add_f32_e32 v7, v21, v7
	global_store_dwordx2 v[10:11], v[16:17], off offset:1024
	s_nop 0
	v_add_f32_dpp v7, v7, v7 quad_perm:[1,0,3,2] row_mask:0xf bank_mask:0xf bound_ctrl:1
	s_nop 1
	v_add_f32_dpp v7, v7, v7 quad_perm:[2,3,0,1] row_mask:0xf bank_mask:0xf bound_ctrl:1
	s_nop 1
	v_add_f32_dpp v7, v7, v7 row_half_mirror row_mask:0xf bank_mask:0xf bound_ctrl:1
	s_nop 1
	v_add_f32_dpp v7, v7, v7 row_mirror row_mask:0xf bank_mask:0xf bound_ctrl:1
	s_nop 0
	v_readlane_b32 s2, v7, 16
	v_readlane_b32 s3, v7, 48
	v_readlane_b32 s0, v7, 0
	v_readlane_b32 s1, v7, 32
	v_mov_b32_e32 v14, s2
	v_mov_b32_e32 v15, s3
	v_pk_add_f32 v[14:15], s[0:1], v[14:15]
	s_nop 0
	v_add_f32_e32 v7, v14, v15
	v_fmamk_f32 v7, v7, 0x3b800000, v226
	v_mul_f32_e32 v14, 0x4b800000, v7
	v_cmp_gt_f32_e32 vcc, s4, v7
	s_nop 1
	v_cndmask_b32_e32 v7, v7, v14, vcc
	v_rsq_f32_e32 v7, v7
	s_nop 0
	v_mul_f32_e32 v14, 0x45800000, v7
	v_cndmask_b32_e32 v7, v7, v14, vcc
	v_mul_f32_e32 v14, v1, v7
	v_pk_mul_f32 v[16:17], v[18:19], v[14:15] op_sel_hi:[1,0]
	v_pk_mul_f32 v[12:13], v[12:13], v[14:15] op_sel_hi:[1,0]
	v_pk_mul_f32 v[14:15], v[2:3], v[16:17]
	v_pk_mul_f32 v[12:13], v[4:5], v[12:13]
	v_cvt_pk_bf16_f32 v14, v14, v15
	s_nop 0
	v_cvt_pk_bf16_f32 v15, v12, v13
	global_store_dwordx2 v[10:11], v[14:15], off offset:1536
	s_branch .LBB0_724
